# static s_setprio 1 for waves 0-3 (the non-skewed half) at each attention unit start
# speedup vs baseline: 1.0039x; 1.0039x over previous
; template <int MODE>
; DI void attn_unit(LAS unsigned char* lds, const bf16_t* Qg, int ldq, const bf16_t* Kg, int ldk, const bf16_t* VTg, int ldvt, bf16_t* Og, int ldo,
;                   int q0, int NT, const float* gout, const float* relb, float lam, float osc, const float* qgain) {
;     ...
;     const bool skew = (MODE != 2) && (wid >= 4);
; __global__ void __launch_bounds__(512, 2) mk_fwd(Args a) {
;     ...
;                 const int b = bh >> 2, h = bh & 3;
;                 int code;
;                 { const unsigned char tab[32] = {15, 14, 16 + 7, 13, 12, 16 + 6, 11, 10, 16 + 5, 9, 8, 16 + 4, 7, 16 + 3, 6, 32 + 7, 32 + 6, 32 + 5, 32 + 4, 32 + 3, 32 + 2, 32 + 1,
;                                                  5, 16 + 2, 4, 3, 32 + 0, 16 + 1, 2, 1, 16 + 0, 0}; code = tab[cls]; }
;                 const int typ = code >> 4, lvl = code & 15, grp = typ == 1 ? 0 : (typ == 2 ? 3 : 1);
;                 if (PROBE_ATT_ONLY >= 0 && dup && typ != PROBE_ATT_ONLY) continue;
;                 const size_t rb = (size_t)b * SEQ;
;                 if (grp == 0) at::attn_unit<1>(lds, QM + rb * 512 + h * 96, 512, KM + rb * 384 + h * 96, 384, VTM + (size_t)(h * 64) * MT + rb, MT, Y + rb * DM + 768 + h * 64, DM,
;                                                256 * lvl, 4 * lvl + 4, a.in[16] + l * 64, nullptr, 0.f, 1.f, a.in[14] + l * 96);
;                 else if (grp == 3) { const int hp = h >> 1, i = 2 * lvl + (h & 1);
;                     at::attn_unit<2>(lds, PROJ + rb * LDP + 1024 + hp * 128, LDP, PROJ + rb * LDP + 1280 + hp * 128, LDP, VT + (size_t)(512 + hp * 128) * MT + rb, MT, Y + rb * DM + 512 + hp * 128, DM,
;                                      128 * i, 2 * i + 2, a.in[9] + l * 64, nullptr, 0.f, 1.f, nullptr); }
.LBB0_103:
	s_mov_b64 s[4:5], -1
	s_and_b64 vcc, exec, s[0:1]
	s_cbranch_vccz .LBB0_97
	v_readfirstlane_b32 s0, v229
	s_nop 3
	s_cmpk_ge_u32 s0, 0x100
	s_cbranch_scc1 .Lprio_skip
	s_setprio 1
.Lprio_skip:
	v_writelane_b32 v254, s6, 36
	s_lshr_b32 s16, s2, 2
	s_and_b32 s0, s2, 3
	s_ashr_i32 s4, s3, 31
	v_writelane_b32 v254, s0, 18
	s_getpc_b64 s[0:1]
	s_add_u32 s0, s0, __const._Z6mk_fwd4Args.tab@rel32@lo+4
	s_addc_u32 s1, s1, __const._Z6mk_fwd4Args.tab@rel32@hi+12
	s_add_u32 s0, s0, s3
	s_addc_u32 s1, s1, s4
	global_load_ubyte v0, v1, s[0:1]
	s_waitcnt vmcnt(0)
	v_readfirstlane_b32 s0, v0
	s_lshr_b32 s1, s0, 4
	s_and_b32 s29, s0, 15
	s_cmp_eq_u32 s1, 2
	s_cselect_b32 s0, 3, 1
	s_cmp_lg_u32 s1, 1
	s_cselect_b32 s3, s0, 0
	s_lshl_b64 s[0:1], s[16:17], 11
	v_writelane_b32 v254, s0, 38
	s_cmp_gt_i32 s3, 2
	s_nop 0
	v_writelane_b32 v254, s1, 39
	s_mov_b64 s[0:1], -1
	s_cbranch_scc0 .LBB0_142
	v_writelane_b32 v254, s3, 40
	s_lshl_b32 s0, s29, 1
	s_and_b32 s3, s2, 1
	s_or_b32 s12, s0, s3
	s_lshl_b64 s[4:5], s[16:17], 23
	v_readlane_b32 s0, v254, 2
	v_readlane_b32 s1, v254, 3
	s_add_u32 s0, s0, s4
	v_readlane_b32 s6, v254, 18
	s_addc_u32 s1, s1, s5
	s_lshl_b32 s6, s6, 6
	s_and_b32 s14, s6, 0x80
	s_lshl_b32 s6, s14, 1
	v_mov_b32_e32 v14, v229
	v_writelane_b32 v254, s6, 42
	s_add_u32 s6, s0, s6
	s_addc_u32 s7, s1, 0
	v_readfirstlane_b32 s0, v14
	s_ashr_i32 s11, s0, 6
	s_ashr_i32 s10, s0, 8
	s_lshl_b32 s0, s11, 5
	s_lshl_b32 s15, s12, 7
	s_and_b32 s0, s0, 0x60
	v_and_b32_e32 v15, 31, v14
	s_or_b32 s13, s0, s15
	v_or_b32_e32 v0, s13, v15
	v_lshlrev_b32_e32 v2, 12, v0
	v_mov_b32_e32 v3, v1
	s_lshl_b32 s22, s10, 6
	v_bfe_u32 v16, v14, 5, 1
	v_lshl_add_u64 v[2:3], s[6:7], 0, v[2:3]
	s_ashr_i32 s23, s22, 31
	v_lshl_add_u64 v[4:5], s[22:23], 1, v[2:3]
	v_lshlrev_b32_e32 v2, 4, v16
	v_mov_b32_e32 v3, v1
	v_lshl_add_u64 v[4:5], v[4:5], 0, v[2:3]
	flat_load_dwordx4 v[66:69], v[4:5] offset:2048
	flat_load_dwordx4 v[70:73], v[4:5] offset:2080
	flat_load_dwordx4 v[74:77], v[4:5] offset:2112
	flat_load_dwordx4 v[78:81], v[4:5] offset:2144
	s_movk_i32 s0, 0x400
	v_ashrrev_i32_e32 v3, 31, v14
	s_or_b32 s18, s15, 64
	v_cmp_gt_i32_e64 s[40:41], s0, v14
	v_lshrrev_b32_e32 v3, 28, v3
	s_and_saveexec_b64 s[0:1], s[40:41]
	s_cbranch_execz .LBB0_107
	v_add_u32_e32 v4, v14, v3
	v_and_b32_e32 v5, 0x1ffffff0, v4
	v_ashrrev_i32_e32 v4, 4, v4
	v_add_u32_e32 v4, s18, v4
	v_sub_u32_e32 v6, v14, v5
	v_ashrrev_i32_e32 v5, 31, v4
	v_lshlrev_b64 v[4:5], 12, v[4:5]
	v_lshlrev_b32_e32 v6, 3, v6
	v_lshl_add_u64 v[4:5], s[6:7], 0, v[4:5]
	v_ashrrev_i32_e32 v7, 31, v6
	v_lshl_add_u64 v[4:5], v[6:7], 1, v[4:5]
	flat_load_dwordx4 v[82:85], v[4:5] offset:2560
